# v018 + SwiGLU epilogue: the rstd-independent g*u products and first store address are computed before the slot-load wait (while the slot loads are in flight)
# baseline (speedup 1.0000x reference)
; __device__ __forceinline__ unsigned cvt_pk_bf16(float lo, float hi) { const cvt_f32x2_t v = {lo, hi}; const cvt_bf16x2_t b = __builtin_convertvector(v, cvt_bf16x2_t); return __builtin_bit_cast(unsigned, b); }
; __device__ __forceinline__ float silu_mul(float g, float u) { return g * u * __builtin_amdgcn_rcpf(1.0f + __builtin_amdgcn_exp2f(g * -1.4426950408889634f)); }
; __device__ __forceinline__ float rstd_from_slots(const float* slots, int row, int fq) {
;     const f32x4 s4 = *(const f32x4*)(slots + (size_t)row * 16 + 4 * fq);
;     float s = (s4[0] + s4[1]) + (s4[2] + s4[3]);
;     s += __shfl_xor(s, 16); s += __shfl_xor(s, 32);
;     return __builtin_amdgcn_rsqf(s * (1.0f / 1024.0f) + RMS_EPS_F);
; }
;     __device__ __forceinline__ void operator()(const f32x4 (&acc)[2][2][4][2], const Unit& u, int wr, int wc, int fr, int fq) const {
;     ...
;             for (int m = 0; m < 4; ++m) { const int row = row0 + ai * HALF + m * 16;
;                 const float sc = rstd_from_slots(slots, row, fq);
;                 const f32x4 g0 = acc[ai][0][m][0] * sc, g1 = acc[ai][0][m][1] * sc, u0 = acc[ai][1][m][0] * sc, u1 = acc[ai][1][m][1] * sc;
;                 u32x4 w; w.x = cvt_pk_bf16(silu_mul(g0[0], u0[0]), silu_mul(g0[1], u0[1])); w.y = cvt_pk_bf16(silu_mul(g0[2], u0[2]), silu_mul(g0[3], u0[3]));
;                 w.z = cvt_pk_bf16(silu_mul(g1[0], u1[0]), silu_mul(g1[1], u1[1])); w.w = cvt_pk_bf16(silu_mul(g1[2], u1[2]), silu_mul(g1[3], u1[3]));
;                 __builtin_nontemporal_store(w, (u32x4*)(O + (size_t)row * ldc + col0)); }
.LBB0_675:
	v_xor_b32_e32 v216, 16, v161
	v_xor_b32_e32 v217, 32, v161
	v_lshlrev_b32_e32 v216, 2, v216
	v_lshlrev_b32_e32 v217, 2, v217
	v_lshl_add_u32 v150, s0, 8, v152
	v_lshl_or_b32 v148, s1, 7, v157
	v_mov_b64_e32 v[146:147], s[10:11]
	v_ashrrev_i32_e32 v149, 31, v148
	v_lshlrev_b64 v[148:149], 1, v[148:149]
	s_andn2_b64 vcc, exec, s[2:3]
	v_mad_i64_i32 v[164:165], s[0:1], v150, s56, v[146:147]
	v_lshl_add_u64 v[164:165], v[164:165], 0, v[148:149]
	s_mov_b64 s[0:1], -1
	s_mov_b32 s98, 0x16000
	s_mov_b32 s99, 0
	v_pk_mul_f32 v[112:113], v[120:121], v[112:113]
	v_pk_mul_f32 v[114:115], v[122:123], v[114:115]
	v_pk_mul_f32 v[116:117], v[124:125], v[116:117]
	v_pk_mul_f32 v[118:119], v[126:127], v[118:119]
	v_pk_mul_f32 v[96:97], v[104:105], v[96:97]
	v_pk_mul_f32 v[98:99], v[106:107], v[98:99]
	v_pk_mul_f32 v[100:101], v[108:109], v[100:101]
	v_pk_mul_f32 v[102:103], v[110:111], v[102:103]
	v_pk_mul_f32 v[80:81], v[88:89], v[80:81]
	v_pk_mul_f32 v[82:83], v[90:91], v[82:83]
	v_pk_mul_f32 v[84:85], v[92:93], v[84:85]
	v_pk_mul_f32 v[86:87], v[94:95], v[86:87]
	v_pk_mul_f32 v[64:65], v[72:73], v[64:65]
	v_pk_mul_f32 v[66:67], v[74:75], v[66:67]
	v_pk_mul_f32 v[68:69], v[76:77], v[68:69]
	v_pk_mul_f32 v[70:71], v[78:79], v[70:71]
	v_pk_mul_f32 v[48:49], v[56:57], v[48:49]
	v_pk_mul_f32 v[50:51], v[58:59], v[50:51]
	v_pk_mul_f32 v[52:53], v[60:61], v[52:53]
	v_pk_mul_f32 v[54:55], v[62:63], v[54:55]
	v_pk_mul_f32 v[32:33], v[40:41], v[32:33]
	v_pk_mul_f32 v[34:35], v[42:43], v[34:35]
	v_pk_mul_f32 v[36:37], v[44:45], v[36:37]
	v_pk_mul_f32 v[38:39], v[46:47], v[38:39]
	v_pk_mul_f32 v[16:17], v[24:25], v[16:17]
	v_pk_mul_f32 v[18:19], v[26:27], v[18:19]
	v_pk_mul_f32 v[20:21], v[28:29], v[20:21]
	v_pk_mul_f32 v[22:23], v[30:31], v[22:23]
	v_pk_mul_f32 v[0:1], v[8:9], v[0:1]
	v_pk_mul_f32 v[2:3], v[10:11], v[2:3]
	v_pk_mul_f32 v[4:5], v[12:13], v[4:5]
	v_pk_mul_f32 v[6:7], v[14:15], v[6:7]
	s_waitcnt vmcnt(0)
	v_add_f32_e32 v172, v172, v173
	v_add_f32_e32 v173, v175, v174
	v_add_f32_e32 v176, v176, v177
	v_add_f32_e32 v177, v179, v178
	v_add_f32_e32 v180, v180, v181
	v_add_f32_e32 v181, v183, v182
	v_add_f32_e32 v184, v184, v185
	v_add_f32_e32 v185, v187, v186
	v_add_f32_e32 v188, v188, v189
	v_add_f32_e32 v189, v191, v190
	v_add_f32_e32 v192, v192, v193
	v_add_f32_e32 v193, v195, v194
	v_add_f32_e32 v196, v196, v197
	v_add_f32_e32 v197, v199, v198
	v_add_f32_e32 v200, v200, v201
	v_add_f32_e32 v201, v203, v202
	v_add_f32_e32 v172, v172, v173
	v_add_f32_e32 v176, v176, v177
	v_add_f32_e32 v180, v180, v181
	v_add_f32_e32 v184, v184, v185
	v_add_f32_e32 v188, v188, v189
	v_add_f32_e32 v192, v192, v193
	v_add_f32_e32 v196, v196, v197
	v_add_f32_e32 v200, v200, v201
	ds_bpermute_b32 v173, v216, v172
	ds_bpermute_b32 v177, v216, v176
	ds_bpermute_b32 v181, v216, v180
	ds_bpermute_b32 v185, v216, v184
	ds_bpermute_b32 v189, v216, v188
	ds_bpermute_b32 v193, v216, v192
	ds_bpermute_b32 v197, v216, v196
	ds_bpermute_b32 v201, v216, v200
	s_waitcnt lgkmcnt(0)
	v_add_f32_e32 v172, v172, v173
	v_add_f32_e32 v176, v176, v177
	v_add_f32_e32 v180, v180, v181
	v_add_f32_e32 v184, v184, v185
	v_add_f32_e32 v188, v188, v189
	v_add_f32_e32 v192, v192, v193
	v_add_f32_e32 v196, v196, v197
	v_add_f32_e32 v200, v200, v201
	ds_bpermute_b32 v173, v217, v172
	ds_bpermute_b32 v177, v217, v176
	ds_bpermute_b32 v181, v217, v180
	ds_bpermute_b32 v185, v217, v184
	ds_bpermute_b32 v189, v217, v188
	ds_bpermute_b32 v193, v217, v192
	ds_bpermute_b32 v197, v217, v196
	ds_bpermute_b32 v201, v217, v200
	s_waitcnt lgkmcnt(0)
	v_add_f32_e32 v172, v172, v173
	v_add_f32_e32 v176, v176, v177
	v_add_f32_e32 v180, v180, v181
	v_add_f32_e32 v184, v184, v185
	v_add_f32_e32 v188, v188, v189
	v_add_f32_e32 v192, v192, v193
	v_add_f32_e32 v196, v196, v197
	v_add_f32_e32 v200, v200, v201
	v_fmamk_f32 v173, v172, 0x3a800000, v162
	v_fmamk_f32 v177, v176, 0x3a800000, v162
	v_fmamk_f32 v181, v180, 0x3a800000, v162
	v_fmamk_f32 v185, v184, 0x3a800000, v162
	v_fmamk_f32 v189, v188, 0x3a800000, v162
	v_fmamk_f32 v193, v192, 0x3a800000, v162
	v_fmamk_f32 v197, v196, 0x3a800000, v162
	v_fmamk_f32 v201, v200, 0x3a800000, v162
	v_rsq_f32_e32 v172, v173
	v_rsq_f32_e32 v176, v177
	v_rsq_f32_e32 v180, v181
	v_rsq_f32_e32 v184, v185
	v_rsq_f32_e32 v188, v189
	v_rsq_f32_e32 v192, v193
	v_rsq_f32_e32 v196, v197
	v_rsq_f32_e32 v200, v201
	v_mul_f32_e32 v172, 0xbfb8aa3b, v172
	v_mul_f32_e32 v176, 0xbfb8aa3b, v176
	v_mul_f32_e32 v180, 0xbfb8aa3b, v180
	v_mul_f32_e32 v184, 0xbfb8aa3b, v184
	v_mul_f32_e32 v188, 0xbfb8aa3b, v188
	v_mul_f32_e32 v192, 0xbfb8aa3b, v192
	v_mul_f32_e32 v196, 0xbfb8aa3b, v196
	v_mul_f32_e32 v200, 0xbfb8aa3b, v200
	v_mul_f32_e32 v120, v172, v120
	v_mul_f32_e32 v121, v172, v121
	v_mul_f32_e32 v122, v172, v122
	v_mul_f32_e32 v123, v172, v123
	v_mul_f32_e32 v124, v172, v124
	v_mul_f32_e32 v125, v172, v125
	v_mul_f32_e32 v126, v172, v126
	v_mul_f32_e32 v127, v172, v127
	v_exp_f32_e32 v120, v120
	v_exp_f32_e32 v121, v121
	v_exp_f32_e32 v122, v122
	v_exp_f32_e32 v123, v123
	v_exp_f32_e32 v124, v124
	v_exp_f32_e32 v125, v125
	v_exp_f32_e32 v126, v126
	v_exp_f32_e32 v127, v127
	v_fma_f32 v120, v120, v173, v173
	v_fma_f32 v121, v121, v173, v173
	v_fma_f32 v122, v122, v173, v173
	v_fma_f32 v123, v123, v173, v173
	v_fma_f32 v124, v124, v173, v173
	v_fma_f32 v125, v125, v173, v173
	v_fma_f32 v126, v126, v173, v173
	v_fma_f32 v127, v127, v173, v173
	v_rcp_f32_e32 v120, v120
	v_rcp_f32_e32 v121, v121
	v_rcp_f32_e32 v122, v122
	v_rcp_f32_e32 v123, v123
	v_rcp_f32_e32 v124, v124
	v_rcp_f32_e32 v125, v125
	v_rcp_f32_e32 v126, v126
	v_rcp_f32_e32 v127, v127
	v_pk_mul_f32 v[112:113], v[112:113], v[120:121]
; __device__ __forceinline__ unsigned cvt_pk_bf16(float lo, float hi) { const cvt_f32x2_t v = {lo, hi}; const cvt_bf16x2_t b = __builtin_convertvector(v, cvt_bf16x2_t); return __builtin_bit_cast(unsigned, b); }
; __device__ __forceinline__ float silu_mul(float g, float u) { return g * u * __builtin_amdgcn_rcpf(1.0f + __builtin_amdgcn_exp2f(g * -1.4426950408889634f)); }
;     __device__ __forceinline__ void operator()(const f32x4 (&acc)[2][2][4][2], const Unit& u, int wr, int wc, int fr, int fq) const {
;     ...
;             for (int m = 0; m < 4; ++m) { const int row = row0 + ai * HALF + m * 16;
;                 const float sc = rstd_from_slots(slots, row, fq);
;                 const f32x4 g0 = acc[ai][0][m][0] * sc, g1 = acc[ai][0][m][1] * sc, u0 = acc[ai][1][m][0] * sc, u1 = acc[ai][1][m][1] * sc;
;                 u32x4 w; w.x = cvt_pk_bf16(silu_mul(g0[0], u0[0]), silu_mul(g0[1], u0[1])); w.y = cvt_pk_bf16(silu_mul(g0[2], u0[2]), silu_mul(g0[3], u0[3]));
;                 w.z = cvt_pk_bf16(silu_mul(g1[0], u1[0]), silu_mul(g1[1], u1[1])); w.w = cvt_pk_bf16(silu_mul(g1[2], u1[2]), silu_mul(g1[3], u1[3]));
;                 __builtin_nontemporal_store(w, (u32x4*)(O + (size_t)row * ldc + col0)); }
	v_pk_mul_f32 v[114:115], v[114:115], v[122:123]
	v_pk_mul_f32 v[116:117], v[116:117], v[124:125]
	v_pk_mul_f32 v[118:119], v[118:119], v[126:127]
	v_cvt_pk_bf16_f32 v120, v116, v117
	v_cvt_pk_bf16_f32 v121, v118, v119
	v_cvt_pk_bf16_f32 v122, v112, v113
	v_cvt_pk_bf16_f32 v123, v114, v115
	global_store_dwordx4 v[164:165], v[120:123], off nt
	v_lshl_add_u64 v[166:167], v[164:165], 0, s[98:99]
	v_mul_f32_e32 v104, v176, v104
	v_mul_f32_e32 v105, v176, v105
	v_mul_f32_e32 v106, v176, v106
	v_mul_f32_e32 v107, v176, v107
	v_mul_f32_e32 v108, v176, v108
	v_mul_f32_e32 v109, v176, v109
	v_mul_f32_e32 v110, v176, v110
	v_mul_f32_e32 v111, v176, v111
	v_exp_f32_e32 v104, v104
	v_exp_f32_e32 v105, v105
	v_exp_f32_e32 v106, v106
	v_exp_f32_e32 v107, v107
	v_exp_f32_e32 v108, v108
	v_exp_f32_e32 v109, v109
	v_exp_f32_e32 v110, v110
	v_exp_f32_e32 v111, v111
	v_fma_f32 v104, v104, v177, v177
	v_fma_f32 v105, v105, v177, v177
	v_fma_f32 v106, v106, v177, v177
	v_fma_f32 v107, v107, v177, v177
	v_fma_f32 v108, v108, v177, v177
	v_fma_f32 v109, v109, v177, v177
	v_fma_f32 v110, v110, v177, v177
	v_fma_f32 v111, v111, v177, v177
	v_rcp_f32_e32 v104, v104
	v_rcp_f32_e32 v105, v105
	v_rcp_f32_e32 v106, v106
	v_rcp_f32_e32 v107, v107
	v_rcp_f32_e32 v108, v108
	v_rcp_f32_e32 v109, v109
	v_rcp_f32_e32 v110, v110
	v_rcp_f32_e32 v111, v111
	v_pk_mul_f32 v[96:97], v[96:97], v[104:105]
	v_pk_mul_f32 v[98:99], v[98:99], v[106:107]
	v_pk_mul_f32 v[100:101], v[100:101], v[108:109]
	v_pk_mul_f32 v[102:103], v[102:103], v[110:111]
	v_cvt_pk_bf16_f32 v104, v100, v101
	v_cvt_pk_bf16_f32 v105, v102, v103
	v_cvt_pk_bf16_f32 v106, v96, v97
	v_cvt_pk_bf16_f32 v107, v98, v99
	global_store_dwordx4 v[166:167], v[104:107], off nt
	v_lshl_add_u64 v[164:165], v[166:167], 0, s[98:99]
	v_mul_f32_e32 v88, v180, v88
	v_mul_f32_e32 v89, v180, v89
	v_mul_f32_e32 v90, v180, v90
	v_mul_f32_e32 v91, v180, v91
	v_mul_f32_e32 v92, v180, v92
	v_mul_f32_e32 v93, v180, v93
	v_mul_f32_e32 v94, v180, v94
	v_mul_f32_e32 v95, v180, v95
	v_exp_f32_e32 v88, v88
	v_exp_f32_e32 v89, v89
	v_exp_f32_e32 v90, v90
	v_exp_f32_e32 v91, v91
	v_exp_f32_e32 v92, v92
	v_exp_f32_e32 v93, v93
	v_exp_f32_e32 v94, v94
	v_exp_f32_e32 v95, v95
	v_fma_f32 v88, v88, v181, v181
	v_fma_f32 v89, v89, v181, v181
	v_fma_f32 v90, v90, v181, v181
	v_fma_f32 v91, v91, v181, v181
	v_fma_f32 v92, v92, v181, v181
	v_fma_f32 v93, v93, v181, v181
	v_fma_f32 v94, v94, v181, v181
	v_fma_f32 v95, v95, v181, v181
	v_rcp_f32_e32 v88, v88
	v_rcp_f32_e32 v89, v89
	v_rcp_f32_e32 v90, v90
	v_rcp_f32_e32 v91, v91
	v_rcp_f32_e32 v92, v92
	v_rcp_f32_e32 v93, v93
	v_rcp_f32_e32 v94, v94
	v_rcp_f32_e32 v95, v95
	v_pk_mul_f32 v[80:81], v[80:81], v[88:89]
	v_pk_mul_f32 v[82:83], v[82:83], v[90:91]
	v_pk_mul_f32 v[84:85], v[84:85], v[92:93]
	v_pk_mul_f32 v[86:87], v[86:87], v[94:95]
	v_cvt_pk_bf16_f32 v88, v84, v85
	v_cvt_pk_bf16_f32 v89, v86, v87
	v_cvt_pk_bf16_f32 v90, v80, v81
	v_cvt_pk_bf16_f32 v91, v82, v83
	global_store_dwordx4 v[164:165], v[88:91], off nt
	v_lshl_add_u64 v[166:167], v[164:165], 0, s[98:99]
	v_mul_f32_e32 v72, v184, v72
	v_mul_f32_e32 v73, v184, v73
	v_mul_f32_e32 v74, v184, v74
	v_mul_f32_e32 v75, v184, v75
	v_mul_f32_e32 v76, v184, v76
	v_mul_f32_e32 v77, v184, v77
	v_mul_f32_e32 v78, v184, v78
	v_mul_f32_e32 v79, v184, v79
	v_exp_f32_e32 v72, v72
	v_exp_f32_e32 v73, v73
	v_exp_f32_e32 v74, v74
	v_exp_f32_e32 v75, v75
	v_exp_f32_e32 v76, v76
	v_exp_f32_e32 v77, v77
	v_exp_f32_e32 v78, v78
	v_exp_f32_e32 v79, v79
	v_fma_f32 v72, v72, v185, v185
	v_fma_f32 v73, v73, v185, v185
	v_fma_f32 v74, v74, v185, v185
	v_fma_f32 v75, v75, v185, v185
	v_fma_f32 v76, v76, v185, v185
	v_fma_f32 v77, v77, v185, v185
	v_fma_f32 v78, v78, v185, v185
	v_fma_f32 v79, v79, v185, v185
	v_rcp_f32_e32 v72, v72
	v_rcp_f32_e32 v73, v73
	v_rcp_f32_e32 v74, v74
	v_rcp_f32_e32 v75, v75
	v_rcp_f32_e32 v76, v76
	v_rcp_f32_e32 v77, v77
	v_rcp_f32_e32 v78, v78
	v_rcp_f32_e32 v79, v79
	v_pk_mul_f32 v[64:65], v[64:65], v[72:73]
	v_pk_mul_f32 v[66:67], v[66:67], v[74:75]
	v_pk_mul_f32 v[68:69], v[68:69], v[76:77]
	v_pk_mul_f32 v[70:71], v[70:71], v[78:79]
	v_cvt_pk_bf16_f32 v72, v68, v69
	v_cvt_pk_bf16_f32 v73, v70, v71
	v_cvt_pk_bf16_f32 v74, v64, v65
	v_cvt_pk_bf16_f32 v75, v66, v67
	global_store_dwordx4 v[166:167], v[72:75], off nt
	s_mov_b32 s98, 0x6e000
	v_lshl_add_u64 v[164:165], v[166:167], 0, s[98:99]
	s_mov_b32 s98, 0x16000
	v_mul_f32_e32 v56, v188, v56
	v_mul_f32_e32 v57, v188, v57
	v_mul_f32_e32 v58, v188, v58
	v_mul_f32_e32 v59, v188, v59
	v_mul_f32_e32 v60, v188, v60
	v_mul_f32_e32 v61, v188, v61
	v_mul_f32_e32 v62, v188, v62
	v_mul_f32_e32 v63, v188, v63
	v_exp_f32_e32 v56, v56
	v_exp_f32_e32 v57, v57
	v_exp_f32_e32 v58, v58
	v_exp_f32_e32 v59, v59
	v_exp_f32_e32 v60, v60
	v_exp_f32_e32 v61, v61
; __device__ __forceinline__ unsigned cvt_pk_bf16(float lo, float hi) { const cvt_f32x2_t v = {lo, hi}; const cvt_bf16x2_t b = __builtin_convertvector(v, cvt_bf16x2_t); return __builtin_bit_cast(unsigned, b); }
; __device__ __forceinline__ float silu_mul(float g, float u) { return g * u * __builtin_amdgcn_rcpf(1.0f + __builtin_amdgcn_exp2f(g * -1.4426950408889634f)); }
;     __device__ __forceinline__ void operator()(const f32x4 (&acc)[2][2][4][2], const Unit& u, int wr, int wc, int fr, int fq) const {
;     ...
;             for (int m = 0; m < 4; ++m) { const int row = row0 + ai * HALF + m * 16;
;                 const float sc = rstd_from_slots(slots, row, fq);
;                 const f32x4 g0 = acc[ai][0][m][0] * sc, g1 = acc[ai][0][m][1] * sc, u0 = acc[ai][1][m][0] * sc, u1 = acc[ai][1][m][1] * sc;
;                 u32x4 w; w.x = cvt_pk_bf16(silu_mul(g0[0], u0[0]), silu_mul(g0[1], u0[1])); w.y = cvt_pk_bf16(silu_mul(g0[2], u0[2]), silu_mul(g0[3], u0[3]));
;                 w.z = cvt_pk_bf16(silu_mul(g1[0], u1[0]), silu_mul(g1[1], u1[1])); w.w = cvt_pk_bf16(silu_mul(g1[2], u1[2]), silu_mul(g1[3], u1[3]));
;                 __builtin_nontemporal_store(w, (u32x4*)(O + (size_t)row * ldc + col0)); }
	v_exp_f32_e32 v62, v62
	v_exp_f32_e32 v63, v63
	v_fma_f32 v56, v56, v189, v189
	v_fma_f32 v57, v57, v189, v189
	v_fma_f32 v58, v58, v189, v189
	v_fma_f32 v59, v59, v189, v189
	v_fma_f32 v60, v60, v189, v189
	v_fma_f32 v61, v61, v189, v189
	v_fma_f32 v62, v62, v189, v189
	v_fma_f32 v63, v63, v189, v189
	v_rcp_f32_e32 v56, v56
	v_rcp_f32_e32 v57, v57
	v_rcp_f32_e32 v58, v58
	v_rcp_f32_e32 v59, v59
	v_rcp_f32_e32 v60, v60
	v_rcp_f32_e32 v61, v61
	v_rcp_f32_e32 v62, v62
	v_rcp_f32_e32 v63, v63
	v_pk_mul_f32 v[48:49], v[48:49], v[56:57]
	v_pk_mul_f32 v[50:51], v[50:51], v[58:59]
	v_pk_mul_f32 v[52:53], v[52:53], v[60:61]
	v_pk_mul_f32 v[54:55], v[54:55], v[62:63]
	v_cvt_pk_bf16_f32 v56, v52, v53
	v_cvt_pk_bf16_f32 v57, v54, v55
	v_cvt_pk_bf16_f32 v58, v48, v49
	v_cvt_pk_bf16_f32 v59, v50, v51
	global_store_dwordx4 v[164:165], v[56:59], off nt
	v_lshl_add_u64 v[166:167], v[164:165], 0, s[98:99]
	v_mul_f32_e32 v40, v192, v40
	v_mul_f32_e32 v41, v192, v41
	v_mul_f32_e32 v42, v192, v42
	v_mul_f32_e32 v43, v192, v43
	v_mul_f32_e32 v44, v192, v44
	v_mul_f32_e32 v45, v192, v45
	v_mul_f32_e32 v46, v192, v46
	v_mul_f32_e32 v47, v192, v47
	v_exp_f32_e32 v40, v40
	v_exp_f32_e32 v41, v41
	v_exp_f32_e32 v42, v42
	v_exp_f32_e32 v43, v43
	v_exp_f32_e32 v44, v44
	v_exp_f32_e32 v45, v45
	v_exp_f32_e32 v46, v46
	v_exp_f32_e32 v47, v47
	v_fma_f32 v40, v40, v193, v193
	v_fma_f32 v41, v41, v193, v193
	v_fma_f32 v42, v42, v193, v193
	v_fma_f32 v43, v43, v193, v193
	v_fma_f32 v44, v44, v193, v193
	v_fma_f32 v45, v45, v193, v193
	v_fma_f32 v46, v46, v193, v193
	v_fma_f32 v47, v47, v193, v193
	v_rcp_f32_e32 v40, v40
	v_rcp_f32_e32 v41, v41
	v_rcp_f32_e32 v42, v42
	v_rcp_f32_e32 v43, v43
	v_rcp_f32_e32 v44, v44
	v_rcp_f32_e32 v45, v45
	v_rcp_f32_e32 v46, v46
	v_rcp_f32_e32 v47, v47
	v_pk_mul_f32 v[32:33], v[32:33], v[40:41]
	v_pk_mul_f32 v[34:35], v[34:35], v[42:43]
	v_pk_mul_f32 v[36:37], v[36:37], v[44:45]
	v_pk_mul_f32 v[38:39], v[38:39], v[46:47]
	v_cvt_pk_bf16_f32 v40, v36, v37
	v_cvt_pk_bf16_f32 v41, v38, v39
	v_cvt_pk_bf16_f32 v42, v32, v33
	v_cvt_pk_bf16_f32 v43, v34, v35
	global_store_dwordx4 v[166:167], v[40:43], off nt
	v_lshl_add_u64 v[164:165], v[166:167], 0, s[98:99]
	v_mul_f32_e32 v24, v196, v24
	v_mul_f32_e32 v25, v196, v25
	v_mul_f32_e32 v26, v196, v26
	v_mul_f32_e32 v27, v196, v27
	v_mul_f32_e32 v28, v196, v28
	v_mul_f32_e32 v29, v196, v29
	v_mul_f32_e32 v30, v196, v30
	v_mul_f32_e32 v31, v196, v31
	v_exp_f32_e32 v24, v24
	v_exp_f32_e32 v25, v25
	v_exp_f32_e32 v26, v26
	v_exp_f32_e32 v27, v27
	v_exp_f32_e32 v28, v28
	v_exp_f32_e32 v29, v29
	v_exp_f32_e32 v30, v30
	v_exp_f32_e32 v31, v31
	v_fma_f32 v24, v24, v197, v197
	v_fma_f32 v25, v25, v197, v197
	v_fma_f32 v26, v26, v197, v197
	v_fma_f32 v27, v27, v197, v197
	v_fma_f32 v28, v28, v197, v197
	v_fma_f32 v29, v29, v197, v197
	v_fma_f32 v30, v30, v197, v197
	v_fma_f32 v31, v31, v197, v197
	v_rcp_f32_e32 v24, v24
	v_rcp_f32_e32 v25, v25
	v_rcp_f32_e32 v26, v26
	v_rcp_f32_e32 v27, v27
	v_rcp_f32_e32 v28, v28
	v_rcp_f32_e32 v29, v29
	v_rcp_f32_e32 v30, v30
	v_rcp_f32_e32 v31, v31
	v_pk_mul_f32 v[16:17], v[16:17], v[24:25]
	v_pk_mul_f32 v[18:19], v[18:19], v[26:27]
	v_pk_mul_f32 v[20:21], v[20:21], v[28:29]
	v_pk_mul_f32 v[22:23], v[22:23], v[30:31]
	v_cvt_pk_bf16_f32 v24, v20, v21
	v_cvt_pk_bf16_f32 v25, v22, v23
	v_cvt_pk_bf16_f32 v26, v16, v17
	v_cvt_pk_bf16_f32 v27, v18, v19
	global_store_dwordx4 v[164:165], v[24:27], off nt
	v_lshl_add_u64 v[166:167], v[164:165], 0, s[98:99]
	v_mul_f32_e32 v8, v200, v8
	v_mul_f32_e32 v9, v200, v9
	v_mul_f32_e32 v10, v200, v10
	v_mul_f32_e32 v11, v200, v11
	v_mul_f32_e32 v12, v200, v12
	v_mul_f32_e32 v13, v200, v13
	v_mul_f32_e32 v14, v200, v14
	v_mul_f32_e32 v15, v200, v15
	v_exp_f32_e32 v8, v8
	v_exp_f32_e32 v9, v9
	v_exp_f32_e32 v10, v10
	v_exp_f32_e32 v11, v11
	v_exp_f32_e32 v12, v12
	v_exp_f32_e32 v13, v13
	v_exp_f32_e32 v14, v14
	v_exp_f32_e32 v15, v15
	v_fma_f32 v8, v8, v201, v201
	v_fma_f32 v9, v9, v201, v201
	v_fma_f32 v10, v10, v201, v201
	v_fma_f32 v11, v11, v201, v201
	v_fma_f32 v12, v12, v201, v201
	v_fma_f32 v13, v13, v201, v201
	v_fma_f32 v14, v14, v201, v201
	v_fma_f32 v15, v15, v201, v201
	v_rcp_f32_e32 v8, v8
	v_rcp_f32_e32 v9, v9
	v_rcp_f32_e32 v10, v10
	v_rcp_f32_e32 v11, v11
	v_rcp_f32_e32 v12, v12
	v_rcp_f32_e32 v13, v13
	v_rcp_f32_e32 v14, v14
	v_rcp_f32_e32 v15, v15
	v_pk_mul_f32 v[0:1], v[0:1], v[8:9]
	v_pk_mul_f32 v[2:3], v[2:3], v[10:11]
	v_pk_mul_f32 v[4:5], v[4:5], v[12:13]
	v_pk_mul_f32 v[6:7], v[6:7], v[14:15]
	v_cvt_pk_bf16_f32 v8, v4, v5
	v_cvt_pk_bf16_f32 v9, v6, v7
	v_cvt_pk_bf16_f32 v10, v0, v1
	v_cvt_pk_bf16_f32 v11, v2, v3
	global_store_dwordx4 v[166:167], v[8:11], off nt
	s_cbranch_vccnz .LBB0_668
	s_andn2_b64 vcc, exec, s[6:7]
	s_cbranch_vccnz .LBB0_667
	s_barrier
	s_branch .LBB0_667

; __device__ __forceinline__ unsigned cvt_pk_bf16(float lo, float hi) { const cvt_f32x2_t v = {lo, hi}; const cvt_bf16x2_t b = __builtin_convertvector(v, cvt_bf16x2_t); return __builtin_bit_cast(unsigned, b); }
; __device__ __forceinline__ float silu_mul(float g, float u) { return g * u * __builtin_amdgcn_rcpf(1.0f + __builtin_amdgcn_exp2f(g * -1.4426950408889634f)); }
; __device__ __forceinline__ float rstd_from_slots(const float* slots, int row, int fq) {
;     const f32x4 s4 = *(const f32x4*)(slots + (size_t)row * 16 + 4 * fq);
;     float s = (s4[0] + s4[1]) + (s4[2] + s4[3]);
;     s += __shfl_xor(s, 16); s += __shfl_xor(s, 32);
;     return __builtin_amdgcn_rsqf(s * (1.0f / 1024.0f) + RMS_EPS_F);
; }
;     __device__ __forceinline__ void operator()(const f32x4 (&acc)[2][2][4][2], const Unit& u, int wr, int wc, int fr, int fq) const {
;     ...
;             for (int m = 0; m < 4; ++m) { const int row = row0 + ai * HALF + m * 16;
;                 const float sc = rstd_from_slots(slots, row, fq);
;                 const f32x4 g0 = acc[ai][0][m][0] * sc, g1 = acc[ai][0][m][1] * sc, u0 = acc[ai][1][m][0] * sc, u1 = acc[ai][1][m][1] * sc;
;                 u32x4 w; w.x = cvt_pk_bf16(silu_mul(g0[0], u0[0]), silu_mul(g0[1], u0[1])); w.y = cvt_pk_bf16(silu_mul(g0[2], u0[2]), silu_mul(g0[3], u0[3]));
;                 w.z = cvt_pk_bf16(silu_mul(g1[0], u1[0]), silu_mul(g1[1], u1[1])); w.w = cvt_pk_bf16(silu_mul(g1[2], u1[2]), silu_mul(g1[3], u1[3]));
;                 __builtin_nontemporal_store(w, (u32x4*)(O + (size_t)row * ldc + col0)); }
.LBB0_1114:
	v_xor_b32_e32 v216, 16, v160
	v_xor_b32_e32 v217, 32, v160
	v_lshlrev_b32_e32 v216, 2, v216
	v_lshlrev_b32_e32 v217, 2, v217
	v_lshl_add_u32 v150, s0, 8, v152
	v_lshl_or_b32 v148, s1, 7, v156
	v_mov_b64_e32 v[146:147], s[10:11]
	v_ashrrev_i32_e32 v149, 31, v148
	v_lshlrev_b64 v[148:149], 1, v[148:149]
	s_andn2_b64 vcc, exec, s[2:3]
	v_mad_i64_i32 v[164:165], s[0:1], v150, s56, v[146:147]
	v_lshl_add_u64 v[164:165], v[164:165], 0, v[148:149]
	s_mov_b64 s[0:1], -1
	s_mov_b32 s98, 0x16000
	s_mov_b32 s99, 0
	v_pk_mul_f32 v[112:113], v[120:121], v[112:113]
	v_pk_mul_f32 v[114:115], v[122:123], v[114:115]
	v_pk_mul_f32 v[116:117], v[124:125], v[116:117]
	v_pk_mul_f32 v[118:119], v[126:127], v[118:119]
	v_pk_mul_f32 v[96:97], v[104:105], v[96:97]
	v_pk_mul_f32 v[98:99], v[106:107], v[98:99]
	v_pk_mul_f32 v[100:101], v[108:109], v[100:101]
	v_pk_mul_f32 v[102:103], v[110:111], v[102:103]
	v_pk_mul_f32 v[80:81], v[88:89], v[80:81]
	v_pk_mul_f32 v[82:83], v[90:91], v[82:83]
	v_pk_mul_f32 v[84:85], v[92:93], v[84:85]
	v_pk_mul_f32 v[86:87], v[94:95], v[86:87]
	v_pk_mul_f32 v[64:65], v[72:73], v[64:65]
	v_pk_mul_f32 v[66:67], v[74:75], v[66:67]
	v_pk_mul_f32 v[68:69], v[76:77], v[68:69]
	v_pk_mul_f32 v[70:71], v[78:79], v[70:71]
	v_pk_mul_f32 v[48:49], v[56:57], v[48:49]
	v_pk_mul_f32 v[50:51], v[58:59], v[50:51]
	v_pk_mul_f32 v[52:53], v[60:61], v[52:53]
	v_pk_mul_f32 v[54:55], v[62:63], v[54:55]
	v_pk_mul_f32 v[32:33], v[40:41], v[32:33]
	v_pk_mul_f32 v[34:35], v[42:43], v[34:35]
	v_pk_mul_f32 v[36:37], v[44:45], v[36:37]
	v_pk_mul_f32 v[38:39], v[46:47], v[38:39]
	v_pk_mul_f32 v[16:17], v[24:25], v[16:17]
	v_pk_mul_f32 v[18:19], v[26:27], v[18:19]
	v_pk_mul_f32 v[20:21], v[28:29], v[20:21]
	v_pk_mul_f32 v[22:23], v[30:31], v[22:23]
	v_pk_mul_f32 v[0:1], v[8:9], v[0:1]
	v_pk_mul_f32 v[2:3], v[10:11], v[2:3]
	v_pk_mul_f32 v[4:5], v[12:13], v[4:5]
	v_pk_mul_f32 v[6:7], v[14:15], v[6:7]
	s_waitcnt vmcnt(0)
	v_add_f32_e32 v172, v172, v173
	v_add_f32_e32 v173, v175, v174
	v_add_f32_e32 v176, v176, v177
	v_add_f32_e32 v177, v179, v178
	v_add_f32_e32 v180, v180, v181
	v_add_f32_e32 v181, v183, v182
	v_add_f32_e32 v184, v184, v185
	v_add_f32_e32 v185, v187, v186
	v_add_f32_e32 v188, v188, v189
	v_add_f32_e32 v189, v191, v190
	v_add_f32_e32 v192, v192, v193
	v_add_f32_e32 v193, v195, v194
	v_add_f32_e32 v196, v196, v197
	v_add_f32_e32 v197, v199, v198
	v_add_f32_e32 v200, v200, v201
	v_add_f32_e32 v201, v203, v202
	v_add_f32_e32 v172, v172, v173
	v_add_f32_e32 v176, v176, v177
	v_add_f32_e32 v180, v180, v181
	v_add_f32_e32 v184, v184, v185
	v_add_f32_e32 v188, v188, v189
	v_add_f32_e32 v192, v192, v193
	v_add_f32_e32 v196, v196, v197
	v_add_f32_e32 v200, v200, v201
	ds_bpermute_b32 v173, v216, v172
	ds_bpermute_b32 v177, v216, v176
	ds_bpermute_b32 v181, v216, v180
	ds_bpermute_b32 v185, v216, v184
	ds_bpermute_b32 v189, v216, v188
	ds_bpermute_b32 v193, v216, v192
	ds_bpermute_b32 v197, v216, v196
	ds_bpermute_b32 v201, v216, v200
	s_waitcnt lgkmcnt(0)
	v_add_f32_e32 v172, v172, v173
	v_add_f32_e32 v176, v176, v177
	v_add_f32_e32 v180, v180, v181
	v_add_f32_e32 v184, v184, v185
	v_add_f32_e32 v188, v188, v189
	v_add_f32_e32 v192, v192, v193
	v_add_f32_e32 v196, v196, v197
	v_add_f32_e32 v200, v200, v201
	ds_bpermute_b32 v173, v217, v172
	ds_bpermute_b32 v177, v217, v176
	ds_bpermute_b32 v181, v217, v180
	ds_bpermute_b32 v185, v217, v184
	ds_bpermute_b32 v189, v217, v188
	ds_bpermute_b32 v193, v217, v192
	ds_bpermute_b32 v197, v217, v196
	ds_bpermute_b32 v201, v217, v200
	s_waitcnt lgkmcnt(0)
	v_add_f32_e32 v172, v172, v173
	v_add_f32_e32 v176, v176, v177
	v_add_f32_e32 v180, v180, v181
	v_add_f32_e32 v184, v184, v185
	v_add_f32_e32 v188, v188, v189
	v_add_f32_e32 v192, v192, v193
	v_add_f32_e32 v196, v196, v197
	v_add_f32_e32 v200, v200, v201
	v_fmamk_f32 v173, v172, 0x3a800000, v161
	v_fmamk_f32 v177, v176, 0x3a800000, v161
	v_fmamk_f32 v181, v180, 0x3a800000, v161
	v_fmamk_f32 v185, v184, 0x3a800000, v161
	v_fmamk_f32 v189, v188, 0x3a800000, v161
	v_fmamk_f32 v193, v192, 0x3a800000, v161
	v_fmamk_f32 v197, v196, 0x3a800000, v161
	v_fmamk_f32 v201, v200, 0x3a800000, v161
	v_rsq_f32_e32 v172, v173
	v_rsq_f32_e32 v176, v177
	v_rsq_f32_e32 v180, v181
	v_rsq_f32_e32 v184, v185
	v_rsq_f32_e32 v188, v189
	v_rsq_f32_e32 v192, v193
	v_rsq_f32_e32 v196, v197
	v_rsq_f32_e32 v200, v201
	v_mul_f32_e32 v172, 0xbfb8aa3b, v172
	v_mul_f32_e32 v176, 0xbfb8aa3b, v176
	v_mul_f32_e32 v180, 0xbfb8aa3b, v180
	v_mul_f32_e32 v184, 0xbfb8aa3b, v184
	v_mul_f32_e32 v188, 0xbfb8aa3b, v188
	v_mul_f32_e32 v192, 0xbfb8aa3b, v192
	v_mul_f32_e32 v196, 0xbfb8aa3b, v196
	v_mul_f32_e32 v200, 0xbfb8aa3b, v200
	v_mul_f32_e32 v120, v172, v120
	v_mul_f32_e32 v121, v172, v121
	v_mul_f32_e32 v122, v172, v122
	v_mul_f32_e32 v123, v172, v123
	v_mul_f32_e32 v124, v172, v124
	v_mul_f32_e32 v125, v172, v125
	v_mul_f32_e32 v126, v172, v126
	v_mul_f32_e32 v127, v172, v127
	v_exp_f32_e32 v120, v120
	v_exp_f32_e32 v121, v121
	v_exp_f32_e32 v122, v122
	v_exp_f32_e32 v123, v123
	v_exp_f32_e32 v124, v124
	v_exp_f32_e32 v125, v125
	v_exp_f32_e32 v126, v126
	v_exp_f32_e32 v127, v127
	v_fma_f32 v120, v120, v173, v173
	v_fma_f32 v121, v121, v173, v173
	v_fma_f32 v122, v122, v173, v173
	v_fma_f32 v123, v123, v173, v173
	v_fma_f32 v124, v124, v173, v173
	v_fma_f32 v125, v125, v173, v173
	v_fma_f32 v126, v126, v173, v173
	v_fma_f32 v127, v127, v173, v173
	v_rcp_f32_e32 v120, v120
	v_rcp_f32_e32 v121, v121
	v_rcp_f32_e32 v122, v122
	v_rcp_f32_e32 v123, v123
	v_rcp_f32_e32 v124, v124
	v_rcp_f32_e32 v125, v125
	v_rcp_f32_e32 v126, v126
	v_rcp_f32_e32 v127, v127
	v_pk_mul_f32 v[112:113], v[112:113], v[120:121]
; __device__ __forceinline__ unsigned cvt_pk_bf16(float lo, float hi) { const cvt_f32x2_t v = {lo, hi}; const cvt_bf16x2_t b = __builtin_convertvector(v, cvt_bf16x2_t); return __builtin_bit_cast(unsigned, b); }
; __device__ __forceinline__ float silu_mul(float g, float u) { return g * u * __builtin_amdgcn_rcpf(1.0f + __builtin_amdgcn_exp2f(g * -1.4426950408889634f)); }
;     __device__ __forceinline__ void operator()(const f32x4 (&acc)[2][2][4][2], const Unit& u, int wr, int wc, int fr, int fq) const {
;     ...
;             for (int m = 0; m < 4; ++m) { const int row = row0 + ai * HALF + m * 16;
;                 const float sc = rstd_from_slots(slots, row, fq);
;                 const f32x4 g0 = acc[ai][0][m][0] * sc, g1 = acc[ai][0][m][1] * sc, u0 = acc[ai][1][m][0] * sc, u1 = acc[ai][1][m][1] * sc;
;                 u32x4 w; w.x = cvt_pk_bf16(silu_mul(g0[0], u0[0]), silu_mul(g0[1], u0[1])); w.y = cvt_pk_bf16(silu_mul(g0[2], u0[2]), silu_mul(g0[3], u0[3]));
;                 w.z = cvt_pk_bf16(silu_mul(g1[0], u1[0]), silu_mul(g1[1], u1[1])); w.w = cvt_pk_bf16(silu_mul(g1[2], u1[2]), silu_mul(g1[3], u1[3]));
;                 __builtin_nontemporal_store(w, (u32x4*)(O + (size_t)row * ldc + col0)); }
	v_pk_mul_f32 v[114:115], v[114:115], v[122:123]
	v_pk_mul_f32 v[116:117], v[116:117], v[124:125]
	v_pk_mul_f32 v[118:119], v[118:119], v[126:127]
	v_cvt_pk_bf16_f32 v120, v116, v117
	v_cvt_pk_bf16_f32 v121, v118, v119
	v_cvt_pk_bf16_f32 v122, v112, v113
	v_cvt_pk_bf16_f32 v123, v114, v115
	global_store_dwordx4 v[164:165], v[120:123], off nt
	v_lshl_add_u64 v[166:167], v[164:165], 0, s[98:99]
	v_mul_f32_e32 v104, v176, v104
	v_mul_f32_e32 v105, v176, v105
	v_mul_f32_e32 v106, v176, v106
	v_mul_f32_e32 v107, v176, v107
	v_mul_f32_e32 v108, v176, v108
	v_mul_f32_e32 v109, v176, v109
	v_mul_f32_e32 v110, v176, v110
	v_mul_f32_e32 v111, v176, v111
	v_exp_f32_e32 v104, v104
	v_exp_f32_e32 v105, v105
	v_exp_f32_e32 v106, v106
	v_exp_f32_e32 v107, v107
	v_exp_f32_e32 v108, v108
	v_exp_f32_e32 v109, v109
	v_exp_f32_e32 v110, v110
	v_exp_f32_e32 v111, v111
	v_fma_f32 v104, v104, v177, v177
	v_fma_f32 v105, v105, v177, v177
	v_fma_f32 v106, v106, v177, v177
	v_fma_f32 v107, v107, v177, v177
	v_fma_f32 v108, v108, v177, v177
	v_fma_f32 v109, v109, v177, v177
	v_fma_f32 v110, v110, v177, v177
	v_fma_f32 v111, v111, v177, v177
	v_rcp_f32_e32 v104, v104
	v_rcp_f32_e32 v105, v105
	v_rcp_f32_e32 v106, v106
	v_rcp_f32_e32 v107, v107
	v_rcp_f32_e32 v108, v108
	v_rcp_f32_e32 v109, v109
	v_rcp_f32_e32 v110, v110
	v_rcp_f32_e32 v111, v111
	v_pk_mul_f32 v[96:97], v[96:97], v[104:105]
	v_pk_mul_f32 v[98:99], v[98:99], v[106:107]
	v_pk_mul_f32 v[100:101], v[100:101], v[108:109]
	v_pk_mul_f32 v[102:103], v[102:103], v[110:111]
	v_cvt_pk_bf16_f32 v104, v100, v101
	v_cvt_pk_bf16_f32 v105, v102, v103
	v_cvt_pk_bf16_f32 v106, v96, v97
	v_cvt_pk_bf16_f32 v107, v98, v99
	global_store_dwordx4 v[166:167], v[104:107], off nt
	v_lshl_add_u64 v[164:165], v[166:167], 0, s[98:99]
	v_mul_f32_e32 v88, v180, v88
	v_mul_f32_e32 v89, v180, v89
	v_mul_f32_e32 v90, v180, v90
	v_mul_f32_e32 v91, v180, v91
	v_mul_f32_e32 v92, v180, v92
	v_mul_f32_e32 v93, v180, v93
	v_mul_f32_e32 v94, v180, v94
	v_mul_f32_e32 v95, v180, v95
	v_exp_f32_e32 v88, v88
	v_exp_f32_e32 v89, v89
	v_exp_f32_e32 v90, v90
	v_exp_f32_e32 v91, v91
	v_exp_f32_e32 v92, v92
	v_exp_f32_e32 v93, v93
	v_exp_f32_e32 v94, v94
	v_exp_f32_e32 v95, v95
	v_fma_f32 v88, v88, v181, v181
	v_fma_f32 v89, v89, v181, v181
	v_fma_f32 v90, v90, v181, v181
	v_fma_f32 v91, v91, v181, v181
	v_fma_f32 v92, v92, v181, v181
	v_fma_f32 v93, v93, v181, v181
	v_fma_f32 v94, v94, v181, v181
	v_fma_f32 v95, v95, v181, v181
	v_rcp_f32_e32 v88, v88
	v_rcp_f32_e32 v89, v89
	v_rcp_f32_e32 v90, v90
	v_rcp_f32_e32 v91, v91
	v_rcp_f32_e32 v92, v92
	v_rcp_f32_e32 v93, v93
	v_rcp_f32_e32 v94, v94
	v_rcp_f32_e32 v95, v95
	v_pk_mul_f32 v[80:81], v[80:81], v[88:89]
	v_pk_mul_f32 v[82:83], v[82:83], v[90:91]
	v_pk_mul_f32 v[84:85], v[84:85], v[92:93]
	v_pk_mul_f32 v[86:87], v[86:87], v[94:95]
	v_cvt_pk_bf16_f32 v88, v84, v85
	v_cvt_pk_bf16_f32 v89, v86, v87
	v_cvt_pk_bf16_f32 v90, v80, v81
	v_cvt_pk_bf16_f32 v91, v82, v83
	global_store_dwordx4 v[164:165], v[88:91], off nt
	v_lshl_add_u64 v[166:167], v[164:165], 0, s[98:99]
	v_mul_f32_e32 v72, v184, v72
	v_mul_f32_e32 v73, v184, v73
	v_mul_f32_e32 v74, v184, v74
	v_mul_f32_e32 v75, v184, v75
	v_mul_f32_e32 v76, v184, v76
	v_mul_f32_e32 v77, v184, v77
	v_mul_f32_e32 v78, v184, v78
	v_mul_f32_e32 v79, v184, v79
	v_exp_f32_e32 v72, v72
	v_exp_f32_e32 v73, v73
	v_exp_f32_e32 v74, v74
	v_exp_f32_e32 v75, v75
	v_exp_f32_e32 v76, v76
	v_exp_f32_e32 v77, v77
	v_exp_f32_e32 v78, v78
	v_exp_f32_e32 v79, v79
	v_fma_f32 v72, v72, v185, v185
	v_fma_f32 v73, v73, v185, v185
	v_fma_f32 v74, v74, v185, v185
	v_fma_f32 v75, v75, v185, v185
	v_fma_f32 v76, v76, v185, v185
	v_fma_f32 v77, v77, v185, v185
	v_fma_f32 v78, v78, v185, v185
	v_fma_f32 v79, v79, v185, v185
	v_rcp_f32_e32 v72, v72
	v_rcp_f32_e32 v73, v73
	v_rcp_f32_e32 v74, v74
	v_rcp_f32_e32 v75, v75
	v_rcp_f32_e32 v76, v76
	v_rcp_f32_e32 v77, v77
	v_rcp_f32_e32 v78, v78
	v_rcp_f32_e32 v79, v79
	v_pk_mul_f32 v[64:65], v[64:65], v[72:73]
	v_pk_mul_f32 v[66:67], v[66:67], v[74:75]
	v_pk_mul_f32 v[68:69], v[68:69], v[76:77]
	v_pk_mul_f32 v[70:71], v[70:71], v[78:79]
	v_cvt_pk_bf16_f32 v72, v68, v69
	v_cvt_pk_bf16_f32 v73, v70, v71
	v_cvt_pk_bf16_f32 v74, v64, v65
	v_cvt_pk_bf16_f32 v75, v66, v67
	global_store_dwordx4 v[166:167], v[72:75], off nt
	s_mov_b32 s98, 0x6e000
	v_lshl_add_u64 v[164:165], v[166:167], 0, s[98:99]
	s_mov_b32 s98, 0x16000
	v_mul_f32_e32 v56, v188, v56
	v_mul_f32_e32 v57, v188, v57
	v_mul_f32_e32 v58, v188, v58
	v_mul_f32_e32 v59, v188, v59
	v_mul_f32_e32 v60, v188, v60
	v_mul_f32_e32 v61, v188, v61
	v_mul_f32_e32 v62, v188, v62
	v_mul_f32_e32 v63, v188, v63
	v_exp_f32_e32 v56, v56
	v_exp_f32_e32 v57, v57
	v_exp_f32_e32 v58, v58
	v_exp_f32_e32 v59, v59
	v_exp_f32_e32 v60, v60
	v_exp_f32_e32 v61, v61
; __device__ __forceinline__ unsigned cvt_pk_bf16(float lo, float hi) { const cvt_f32x2_t v = {lo, hi}; const cvt_bf16x2_t b = __builtin_convertvector(v, cvt_bf16x2_t); return __builtin_bit_cast(unsigned, b); }
; __device__ __forceinline__ float silu_mul(float g, float u) { return g * u * __builtin_amdgcn_rcpf(1.0f + __builtin_amdgcn_exp2f(g * -1.4426950408889634f)); }
;     __device__ __forceinline__ void operator()(const f32x4 (&acc)[2][2][4][2], const Unit& u, int wr, int wc, int fr, int fq) const {
;     ...
;             for (int m = 0; m < 4; ++m) { const int row = row0 + ai * HALF + m * 16;
;                 const float sc = rstd_from_slots(slots, row, fq);
;                 const f32x4 g0 = acc[ai][0][m][0] * sc, g1 = acc[ai][0][m][1] * sc, u0 = acc[ai][1][m][0] * sc, u1 = acc[ai][1][m][1] * sc;
;                 u32x4 w; w.x = cvt_pk_bf16(silu_mul(g0[0], u0[0]), silu_mul(g0[1], u0[1])); w.y = cvt_pk_bf16(silu_mul(g0[2], u0[2]), silu_mul(g0[3], u0[3]));
;                 w.z = cvt_pk_bf16(silu_mul(g1[0], u1[0]), silu_mul(g1[1], u1[1])); w.w = cvt_pk_bf16(silu_mul(g1[2], u1[2]), silu_mul(g1[3], u1[3]));
;                 __builtin_nontemporal_store(w, (u32x4*)(O + (size_t)row * ldc + col0)); }
	v_exp_f32_e32 v62, v62
	v_exp_f32_e32 v63, v63
	v_fma_f32 v56, v56, v189, v189
	v_fma_f32 v57, v57, v189, v189
	v_fma_f32 v58, v58, v189, v189
	v_fma_f32 v59, v59, v189, v189
	v_fma_f32 v60, v60, v189, v189
	v_fma_f32 v61, v61, v189, v189
	v_fma_f32 v62, v62, v189, v189
	v_fma_f32 v63, v63, v189, v189
	v_rcp_f32_e32 v56, v56
	v_rcp_f32_e32 v57, v57
	v_rcp_f32_e32 v58, v58
	v_rcp_f32_e32 v59, v59
	v_rcp_f32_e32 v60, v60
	v_rcp_f32_e32 v61, v61
	v_rcp_f32_e32 v62, v62
	v_rcp_f32_e32 v63, v63
	v_pk_mul_f32 v[48:49], v[48:49], v[56:57]
	v_pk_mul_f32 v[50:51], v[50:51], v[58:59]
	v_pk_mul_f32 v[52:53], v[52:53], v[60:61]
	v_pk_mul_f32 v[54:55], v[54:55], v[62:63]
	v_cvt_pk_bf16_f32 v56, v52, v53
	v_cvt_pk_bf16_f32 v57, v54, v55
	v_cvt_pk_bf16_f32 v58, v48, v49
	v_cvt_pk_bf16_f32 v59, v50, v51
	global_store_dwordx4 v[164:165], v[56:59], off nt
	v_lshl_add_u64 v[166:167], v[164:165], 0, s[98:99]
	v_mul_f32_e32 v40, v192, v40
	v_mul_f32_e32 v41, v192, v41
	v_mul_f32_e32 v42, v192, v42
	v_mul_f32_e32 v43, v192, v43
	v_mul_f32_e32 v44, v192, v44
	v_mul_f32_e32 v45, v192, v45
	v_mul_f32_e32 v46, v192, v46
	v_mul_f32_e32 v47, v192, v47
	v_exp_f32_e32 v40, v40
	v_exp_f32_e32 v41, v41
	v_exp_f32_e32 v42, v42
	v_exp_f32_e32 v43, v43
	v_exp_f32_e32 v44, v44
	v_exp_f32_e32 v45, v45
	v_exp_f32_e32 v46, v46
	v_exp_f32_e32 v47, v47
	v_fma_f32 v40, v40, v193, v193
	v_fma_f32 v41, v41, v193, v193
	v_fma_f32 v42, v42, v193, v193
	v_fma_f32 v43, v43, v193, v193
	v_fma_f32 v44, v44, v193, v193
	v_fma_f32 v45, v45, v193, v193
	v_fma_f32 v46, v46, v193, v193
	v_fma_f32 v47, v47, v193, v193
	v_rcp_f32_e32 v40, v40
	v_rcp_f32_e32 v41, v41
	v_rcp_f32_e32 v42, v42
	v_rcp_f32_e32 v43, v43
	v_rcp_f32_e32 v44, v44
	v_rcp_f32_e32 v45, v45
	v_rcp_f32_e32 v46, v46
	v_rcp_f32_e32 v47, v47
	v_pk_mul_f32 v[32:33], v[32:33], v[40:41]
	v_pk_mul_f32 v[34:35], v[34:35], v[42:43]
	v_pk_mul_f32 v[36:37], v[36:37], v[44:45]
	v_pk_mul_f32 v[38:39], v[38:39], v[46:47]
	v_cvt_pk_bf16_f32 v40, v36, v37
	v_cvt_pk_bf16_f32 v41, v38, v39
	v_cvt_pk_bf16_f32 v42, v32, v33
	v_cvt_pk_bf16_f32 v43, v34, v35
	global_store_dwordx4 v[166:167], v[40:43], off nt
	v_lshl_add_u64 v[164:165], v[166:167], 0, s[98:99]
	v_mul_f32_e32 v24, v196, v24
	v_mul_f32_e32 v25, v196, v25
	v_mul_f32_e32 v26, v196, v26
	v_mul_f32_e32 v27, v196, v27
	v_mul_f32_e32 v28, v196, v28
	v_mul_f32_e32 v29, v196, v29
	v_mul_f32_e32 v30, v196, v30
	v_mul_f32_e32 v31, v196, v31
	v_exp_f32_e32 v24, v24
	v_exp_f32_e32 v25, v25
	v_exp_f32_e32 v26, v26
	v_exp_f32_e32 v27, v27
	v_exp_f32_e32 v28, v28
	v_exp_f32_e32 v29, v29
	v_exp_f32_e32 v30, v30
	v_exp_f32_e32 v31, v31
	v_fma_f32 v24, v24, v197, v197
	v_fma_f32 v25, v25, v197, v197
	v_fma_f32 v26, v26, v197, v197
	v_fma_f32 v27, v27, v197, v197
	v_fma_f32 v28, v28, v197, v197
	v_fma_f32 v29, v29, v197, v197
	v_fma_f32 v30, v30, v197, v197
	v_fma_f32 v31, v31, v197, v197
	v_rcp_f32_e32 v24, v24
	v_rcp_f32_e32 v25, v25
	v_rcp_f32_e32 v26, v26
	v_rcp_f32_e32 v27, v27
	v_rcp_f32_e32 v28, v28
	v_rcp_f32_e32 v29, v29
	v_rcp_f32_e32 v30, v30
	v_rcp_f32_e32 v31, v31
	v_pk_mul_f32 v[16:17], v[16:17], v[24:25]
	v_pk_mul_f32 v[18:19], v[18:19], v[26:27]
	v_pk_mul_f32 v[20:21], v[20:21], v[28:29]
	v_pk_mul_f32 v[22:23], v[22:23], v[30:31]
	v_cvt_pk_bf16_f32 v24, v20, v21
	v_cvt_pk_bf16_f32 v25, v22, v23
	v_cvt_pk_bf16_f32 v26, v16, v17
	v_cvt_pk_bf16_f32 v27, v18, v19
	global_store_dwordx4 v[164:165], v[24:27], off nt
	v_lshl_add_u64 v[166:167], v[164:165], 0, s[98:99]
	v_mul_f32_e32 v8, v200, v8
	v_mul_f32_e32 v9, v200, v9
	v_mul_f32_e32 v10, v200, v10
	v_mul_f32_e32 v11, v200, v11
	v_mul_f32_e32 v12, v200, v12
	v_mul_f32_e32 v13, v200, v13
	v_mul_f32_e32 v14, v200, v14
	v_mul_f32_e32 v15, v200, v15
	v_exp_f32_e32 v8, v8
	v_exp_f32_e32 v9, v9
	v_exp_f32_e32 v10, v10
	v_exp_f32_e32 v11, v11
	v_exp_f32_e32 v12, v12
	v_exp_f32_e32 v13, v13
	v_exp_f32_e32 v14, v14
	v_exp_f32_e32 v15, v15
	v_fma_f32 v8, v8, v201, v201
	v_fma_f32 v9, v9, v201, v201
	v_fma_f32 v10, v10, v201, v201
	v_fma_f32 v11, v11, v201, v201
	v_fma_f32 v12, v12, v201, v201
	v_fma_f32 v13, v13, v201, v201
	v_fma_f32 v14, v14, v201, v201
	v_fma_f32 v15, v15, v201, v201
	v_rcp_f32_e32 v8, v8
	v_rcp_f32_e32 v9, v9
	v_rcp_f32_e32 v10, v10
	v_rcp_f32_e32 v11, v11
	v_rcp_f32_e32 v12, v12
	v_rcp_f32_e32 v13, v13
	v_rcp_f32_e32 v14, v14
	v_rcp_f32_e32 v15, v15
	v_pk_mul_f32 v[0:1], v[0:1], v[8:9]
	v_pk_mul_f32 v[2:3], v[2:3], v[10:11]
	v_pk_mul_f32 v[4:5], v[4:5], v[12:13]
	v_pk_mul_f32 v[6:7], v[6:7], v[14:15]
	v_cvt_pk_bf16_f32 v8, v4, v5
	v_cvt_pk_bf16_f32 v9, v6, v7
	v_cvt_pk_bf16_f32 v10, v0, v1
	v_cvt_pk_bf16_f32 v11, v2, v3
	global_store_dwordx4 v[166:167], v[8:11], off nt
	s_cbranch_vccnz .LBB0_1107
	s_andn2_b64 vcc, exec, s[6:7]
	s_cbranch_vccnz .LBB0_1106
	s_barrier
	s_branch .LBB0_1106
